# LDS-read hoisting also in the stick-breaking tile blocks (waits referring to reads issued before the block are kept with adjusted counts)
# baseline (speedup 1.0000x reference)
.LBB0_461:
	s_xor_b32 s51, s50, 1
	s_waitcnt lgkmcnt(0)
	s_barrier
	v_lshl_add_u32 v41, s51, 5, v107
	ds_read_b32 v41, v41
	s_waitcnt lgkmcnt(0)
	v_cmp_ne_u32_e32 vcc, 0, v41
	s_bcnt1_i32_b64 s90, vcc
	s_cmp_lg_u64 s[90:91], 64
	s_cselect_b64 s[8:9], -1, 0
	s_cmp_eq_u64 s[90:91], 64
	s_cbranch_scc1 .LBB0_472
	s_add_i32 s12, s16, 64
	s_cmp_ge_i32 s12, s18
	s_cbranch_scc1 .LBB0_469
	s_mov_b32 s12, 0xc3200000
	v_cmp_gt_f32_e32 vcc, s12, v40
	s_cmp_eq_u64 vcc, -1
	s_cbranch_scc1 .LBB0_469
	v_add3_u32 v41, s52, v121, v123
	ds_read_b128 v[68:71], v41
	ds_read_b128 v[72:75], v41 offset:64
	ds_read_b128 v[64:67], v41 offset:2304
	ds_read_b128 v[60:63], v41 offset:2368
	ds_read_b128 v[56:59], v41 offset:4608
	ds_read_b128 v[52:55], v41 offset:4672
	ds_read_b128 v[48:51], v41 offset:6912
	ds_read_b128 v[44:47], v41 offset:6976
	s_add_i32 s12, s16, 0x7f
	s_cmp_lt_i32 s12, s17
	s_mov_b64 s[12:13], -1
	s_cbranch_scc1 .LBB0_466
	s_waitcnt lgkmcnt(7)
	v_mfma_f32_16x16x32_bf16 v[76:79], v[68:71], v[8:11], 0
	v_cmp_lt_i32_e32 vcc, 0, v131
	s_mov_b32 s26, s24
	s_mov_b32 s27, s24
	s_waitcnt lgkmcnt(6)
	v_mfma_f32_16x16x32_bf16 v[88:91], v[72:75], v[12:15], v[76:79]
	s_mov_b32 s25, s24
	s_mov_b64 s[12:13], 0
	s_waitcnt lgkmcnt(5)
	v_mfma_f32_16x16x32_bf16 v[76:79], v[64:67], v[8:11], 0
	s_waitcnt lgkmcnt(4)
	v_mfma_f32_16x16x32_bf16 v[84:87], v[60:63], v[12:15], v[76:79]
	s_nop 1
	v_mul_f32_e32 v41, 0x3e38aa3b, v88
	v_cndmask_b32_e32 v98, v214, v41, vcc
	v_exp_f32_e64 v41, -|v98|
	v_cmp_lt_i32_e32 vcc, 1, v131
	v_max_f32_e32 v42, 0, v98
	s_waitcnt lgkmcnt(3)
	v_mfma_f32_16x16x32_bf16 v[76:79], v[56:59], v[8:11], 0
	v_add_f32_e32 v41, 1.0, v41
	v_log_f32_e32 v88, v41
	v_mul_f32_e32 v41, 0x3e38aa3b, v89
	v_cndmask_b32_e32 v99, v214, v41, vcc
	v_exp_f32_e64 v41, -|v99|
	v_cmp_lt_i32_e32 vcc, 2, v131
	v_max_f32_e32 v43, 0, v99
	s_waitcnt lgkmcnt(2)
	v_mfma_f32_16x16x32_bf16 v[80:83], v[52:55], v[12:15], v[76:79]
	v_add_f32_e32 v41, 1.0, v41
	v_log_f32_e32 v89, v41
	v_mul_f32_e32 v41, 0x3e38aa3b, v90
	v_cndmask_b32_e32 v194, v214, v41, vcc
	v_exp_f32_e64 v41, -|v194|
	v_pk_add_f32 v[94:95], v[42:43], v[88:89]
	v_cmp_lt_i32_e32 vcc, 3, v131
	s_waitcnt lgkmcnt(1)
	v_mfma_f32_16x16x32_bf16 v[76:79], v[48:51], v[8:11], 0
	v_add_f32_e32 v41, 1.0, v41
	v_log_f32_e32 v88, v41
	v_mul_f32_e32 v41, 0x3e38aa3b, v91
	v_cndmask_b32_e32 v195, v214, v41, vcc
	v_exp_f32_e64 v41, -|v195|
	v_cmp_lt_i32_e32 vcc, 16, v131
	s_waitcnt lgkmcnt(0)
	v_mfma_f32_16x16x32_bf16 v[76:79], v[44:47], v[12:15], v[76:79]
	v_max_f32_e32 v42, 0, v194
	v_add_f32_e32 v41, 1.0, v41
	v_log_f32_e32 v89, v41
	v_mul_f32_e32 v41, 0x3e38aa3b, v84
	v_cndmask_b32_e32 v224, v214, v41, vcc
	v_exp_f32_e64 v41, -|v224|
	v_cmp_lt_i32_e32 vcc, 17, v131
	v_max_f32_e32 v43, 0, v195
	v_pk_add_f32 v[96:97], v[42:43], v[88:89]
	v_add_f32_e32 v41, 1.0, v41
	v_log_f32_e32 v84, v41
	v_mul_f32_e32 v41, 0x3e38aa3b, v85
	v_cndmask_b32_e32 v225, v214, v41, vcc
	v_exp_f32_e64 v41, -|v225|
	v_cmp_lt_i32_e32 vcc, 18, v131
	v_max_f32_e32 v42, 0, v224
	v_max_f32_e32 v43, 0, v225
	v_add_f32_e32 v41, 1.0, v41
	v_log_f32_e32 v85, v41
	v_mul_f32_e32 v41, 0x3e38aa3b, v86
	v_cndmask_b32_e32 v226, v214, v41, vcc
	v_exp_f32_e64 v41, -|v226|
	v_cmp_lt_i32_e32 vcc, 19, v131
	v_pk_add_f32 v[84:85], v[42:43], v[84:85]
	v_max_f32_e32 v42, 0, v226
	v_add_f32_e32 v41, 1.0, v41
	v_log_f32_e32 v86, v41
	v_mul_f32_e32 v41, 0x3e38aa3b, v87
	v_cndmask_b32_e32 v227, v214, v41, vcc
	v_exp_f32_e64 v41, -|v227|
	v_cmp_lt_i32_e32 vcc, 32, v131
	v_max_f32_e32 v43, 0, v227
	v_mov_b64_e32 v[90:91], s[26:27]
	v_add_f32_e32 v41, 1.0, v41
	v_log_f32_e32 v87, v41
	v_mul_f32_e32 v41, 0x3e38aa3b, v80
	v_cndmask_b32_e32 v92, v214, v41, vcc
	v_exp_f32_e64 v41, -|v92|
	v_cmp_lt_i32_e32 vcc, 33, v131
	v_pk_add_f32 v[86:87], v[42:43], v[86:87]
	v_max_f32_e32 v42, 0, v92
	v_add_f32_e32 v41, 1.0, v41
	v_log_f32_e32 v80, v41
	v_mul_f32_e32 v41, 0x3e38aa3b, v81
	v_cndmask_b32_e32 v93, v214, v41, vcc
	v_exp_f32_e64 v41, -|v93|
	v_cmp_lt_i32_e32 vcc, 34, v131
	v_max_f32_e32 v43, 0, v93
	v_mov_b64_e32 v[88:89], s[24:25]
	v_add_f32_e32 v41, 1.0, v41
	v_log_f32_e32 v81, v41
	v_mul_f32_e32 v41, 0x3e38aa3b, v82
	v_cndmask_b32_e32 v228, v214, v41, vcc
	v_exp_f32_e64 v41, -|v228|
	v_cmp_lt_i32_e32 vcc, 35, v131
	v_pk_add_f32 v[80:81], v[42:43], v[80:81]
	v_max_f32_e32 v42, 0, v228
	v_add_f32_e32 v41, 1.0, v41
	v_log_f32_e32 v82, v41
	v_mul_f32_e32 v41, 0x3e38aa3b, v83
	v_cndmask_b32_e32 v229, v214, v41, vcc
	v_exp_f32_e64 v41, -|v229|
	v_cmp_lt_i32_e32 vcc, 48, v131
	v_max_f32_e32 v43, 0, v229
	v_add_f32_e32 v41, 1.0, v41
	v_log_f32_e32 v83, v41
	v_mul_f32_e32 v41, 0x3e38aa3b, v76
	v_cndmask_b32_e32 v230, v214, v41, vcc
	v_exp_f32_e64 v41, -|v230|
	v_cmp_lt_i32_e32 vcc, 49, v131
	v_pk_add_f32 v[82:83], v[42:43], v[82:83]
	v_max_f32_e32 v42, 0, v230
	v_add_f32_e32 v41, 1.0, v41
	v_log_f32_e32 v76, v41
	v_mul_f32_e32 v41, 0x3e38aa3b, v77
	v_cndmask_b32_e32 v231, v214, v41, vcc
	v_exp_f32_e64 v41, -|v231|
	v_cmp_lt_i32_e32 vcc, 50, v131
	v_max_f32_e32 v43, 0, v231
	v_add_f32_e32 v41, 1.0, v41
	v_log_f32_e32 v77, v41
	v_mul_f32_e32 v41, 0x3e38aa3b, v78
	v_cndmask_b32_e32 v232, v214, v41, vcc
	v_exp_f32_e64 v41, -|v232|
	v_pk_add_f32 v[182:183], v[42:43], v[76:77]
	v_cmp_lt_i32_e32 vcc, 51, v131
	v_max_f32_e32 v42, 0, v232
	v_add_f32_e32 v41, 1.0, v41
	v_log_f32_e32 v76, v41
	v_mul_f32_e32 v41, 0x3e38aa3b, v79
	v_cndmask_b32_e32 v233, v214, v41, vcc
	v_exp_f32_e64 v41, -|v233|
	v_max_f32_e32 v43, 0, v233
	v_add_f32_e32 v41, 1.0, v41
	v_log_f32_e32 v77, v41
	v_mov_b32_e32 v41, v40
	v_pk_add_f32 v[184:185], v[42:43], v[76:77]
	v_pk_add_f32 v[42:43], v[94:95], 0 neg_lo:[1,1] neg_hi:[1,1]
	s_nop 0
	v_cvt_pk_bf16_f32 v196, v42, v43
	v_pk_add_f32 v[42:43], v[96:97], 0 neg_lo:[1,1] neg_hi:[1,1]
	s_nop 0
	v_cvt_pk_bf16_f32 v197, v42, v43
	v_pk_add_f32 v[42:43], v[84:85], 0 neg_lo:[1,1] neg_hi:[1,1]
	s_nop 0
	v_cvt_pk_bf16_f32 v198, v42, v43
	v_pk_add_f32 v[42:43], v[86:87], 0 neg_lo:[1,1] neg_hi:[1,1]
	s_nop 0
	v_cvt_pk_bf16_f32 v199, v42, v43
	v_pk_add_f32 v[42:43], v[80:81], 0 neg_lo:[1,1] neg_hi:[1,1]
	s_nop 0
	v_cvt_pk_bf16_f32 v76, v42, v43
	v_pk_add_f32 v[42:43], v[82:83], 0 neg_lo:[1,1] neg_hi:[1,1]
	s_nop 0
	v_cvt_pk_bf16_f32 v77, v42, v43
	v_pk_add_f32 v[42:43], v[182:183], 0 neg_lo:[1,1] neg_hi:[1,1]
	s_nop 0
	v_cvt_pk_bf16_f32 v78, v42, v43
	v_pk_add_f32 v[42:43], v[184:185], 0 neg_lo:[1,1] neg_hi:[1,1]
	s_nop 0
	v_cvt_pk_bf16_f32 v79, v42, v43
	v_mov_b32_e32 v42, v40
	v_mov_b32_e32 v43, v40
	s_nop 1
	v_mfma_f32_16x16x32_bf16 v[208:211], v[0:3], v[76:79], v[40:43]
	v_mfma_f32_16x16x32_bf16 v[204:207], v[4:7], v[196:199], v[40:43]
	v_mfma_f32_16x16x32_bf16 v[200:203], v[0:3], v[196:199], v[40:43]
	v_mfma_f32_16x16x32_bf16 v[218:221], v[4:7], v[76:79], v[40:43]
	s_nop 2
	v_sub_f32_e32 v41, v92, v80
	v_sub_f32_e32 v42, v93, v81
	v_add_f32_e32 v41, v208, v41
	v_add_f32_e32 v42, v209, v42
	v_exp_f32_e32 v41, v41
	v_exp_f32_e32 v42, v42
	v_sub_f32_e32 v43, v228, v82
	v_sub_f32_e32 v80, v229, v83
	v_mfma_f32_16x16x32_bf16 v[204:207], v[88:91], v[76:79], v[204:207]
	v_add_f32_e32 v43, v210, v43
	v_add_f32_e32 v80, v211, v80
	v_exp_f32_e32 v43, v43
	v_exp_f32_e32 v80, v80
	v_cvt_pk_bf16_f32 v92, v41, v42
	v_sub_f32_e32 v41, v224, v84
	v_sub_f32_e32 v42, v225, v85
	s_nop 0
	v_add_f32_e32 v41, v41, v204
	v_add_f32_e32 v42, v42, v205
	v_cvt_pk_bf16_f32 v93, v43, v80
	v_exp_f32_e32 v41, v41
	v_exp_f32_e32 v42, v42
	v_sub_f32_e32 v43, v226, v86
	v_sub_f32_e32 v80, v227, v87
	v_mfma_f32_16x16x32_bf16 v[200:203], v[88:91], v[76:79], v[200:203]
	v_add_f32_e32 v43, v43, v206
	v_add_f32_e32 v80, v80, v207
	v_exp_f32_e32 v43, v43
	v_exp_f32_e32 v80, v80
	v_cvt_pk_bf16_f32 v204, v41, v42
	v_sub_f32_e32 v41, v98, v94
	v_sub_f32_e32 v42, v99, v95
	s_nop 0
	v_add_f32_e32 v41, v41, v200
	v_add_f32_e32 v42, v42, v201
	v_cvt_pk_bf16_f32 v205, v43, v80
	v_exp_f32_e32 v41, v41
	v_exp_f32_e32 v42, v42
	v_sub_f32_e32 v43, v194, v96
	v_sub_f32_e32 v80, v195, v97
	v_add_f32_e32 v43, v43, v202
	v_add_f32_e32 v80, v80, v203
	v_exp_f32_e32 v43, v43
	v_exp_f32_e32 v80, v80
	v_cvt_pk_bf16_f32 v202, v41, v42
	v_sub_f32_e32 v41, v233, v185
	v_sub_f32_e32 v42, v232, v184
	v_add_f32_e32 v42, v220, v42
	v_add_f32_e32 v41, v221, v41
	v_cvt_pk_bf16_f32 v203, v43, v80
	v_sub_f32_e32 v43, v231, v183
	v_sub_f32_e32 v80, v230, v182
	v_exp_f32_e32 v42, v42
	v_exp_f32_e32 v41, v41
	v_add_f32_e32 v80, v218, v80
	v_add_f32_e32 v43, v219, v43
	v_exp_f32_e32 v80, v80
	v_exp_f32_e32 v43, v43
	v_cvt_pk_bf16_f32 v95, v42, v41
	v_lshlrev_b32_e32 v41, 1, v137
	v_add3_u32 v41, s52, v136, v41
	ds_read_b64_tr_b16 v[234:235], v41 offset:9216
	ds_read_b64_tr_b16 v[238:239], v41 offset:9248
	ds_read_b64_tr_b16 v[236:237], v41 offset:11520
	ds_read_b64_tr_b16 v[240:241], v41 offset:11552
	v_cvt_pk_bf16_f32 v94, v80, v43
	s_nop 0
	s_nop 0
	s_nop 0
	ds_read_b64_tr_b16 v[96:97], v41 offset:13824
	ds_read_b64_tr_b16 v[98:99], v41 offset:16128
	s_nop 0
	s_waitcnt lgkmcnt(3)
	v_mfma_f32_16x16x32_bf16 v[80:83], v[234:237], v[202:205], v[36:39]
	ds_read_b64_tr_b16 v[234:235], v41 offset:13856
	ds_read_b64_tr_b16 v[236:237], v41 offset:16160
	s_nop 0
	s_waitcnt lgkmcnt(2)
	v_mfma_f32_16x16x32_bf16 v[80:83], v[96:99], v[92:95], v[80:83]
	s_nop 0
	s_nop 0
	s_nop 0
	s_nop 0
	v_mfma_f32_16x16x32_bf16 v[84:87], v[238:241], v[202:205], v[32:35]
	ds_read_b64_tr_b16 v[238:239], v41 offset:9280
	ds_read_b64_tr_b16 v[240:241], v41 offset:11584
	v_mfma_f32_16x16x32_bf16 v[194:197], v[88:91], v[196:199], 0
	s_nop 0
	s_waitcnt lgkmcnt(2)
	v_mfma_f32_16x16x32_bf16 v[84:87], v[234:237], v[92:95], v[84:87]
	ds_read_b64_tr_b16 v[234:235], v41 offset:13888
	ds_read_b64_tr_b16 v[236:237], v41 offset:16192
	s_nop 0
	s_nop 0
	s_nop 0
	s_nop 0
	s_nop 0
	s_waitcnt lgkmcnt(2)
	v_mfma_f32_16x16x32_bf16 v[96:99], v[238:241], v[202:205], v[28:31]
	ds_read_b64_tr_b16 v[238:239], v41 offset:9312
	ds_read_b64_tr_b16 v[240:241], v41 offset:11616
	s_nop 0
	s_waitcnt lgkmcnt(2)
	v_mfma_f32_16x16x32_bf16 v[96:99], v[234:237], v[92:95], v[96:99]
	ds_read_b64_tr_b16 v[234:235], v41 offset:13920
	ds_read_b64_tr_b16 v[236:237], v41 offset:16224
	s_nop 0
	s_nop 0
	s_nop 0
	s_nop 0
	s_nop 0
	s_waitcnt lgkmcnt(2)
	v_mfma_f32_16x16x32_bf16 v[198:201], v[238:241], v[202:205], v[24:27]
	v_mfma_f32_16x16x32_bf16 v[76:79], v[88:91], v[76:79], v[194:197]
	s_nop 0
	s_waitcnt lgkmcnt(0)
	v_mfma_f32_16x16x32_bf16 v[92:95], v[234:237], v[92:95], v[198:201]
	s_nop 5
	v_add_f32_e32 v41, v40, v76
	s_waitcnt lgkmcnt(0)
.LBB0_466:
	s_andn2_b64 vcc, exec, s[12:13]
	s_cbranch_vccnz .LBB0_468
	s_waitcnt lgkmcnt(7)
	v_mfma_f32_16x16x32_bf16 v[68:71], v[68:71], v[8:11], 0
	s_mov_b32 s26, s24
	s_mov_b32 s27, s24
	s_mov_b32 s25, s24
	s_waitcnt lgkmcnt(6)
	v_mfma_f32_16x16x32_bf16 v[68:71], v[72:75], v[12:15], v[68:71]
	s_mov_b32 s12, 0x3e38aa3b
	s_waitcnt lgkmcnt(5)
	v_mfma_f32_16x16x32_bf16 v[64:67], v[64:67], v[8:11], 0
	s_waitcnt lgkmcnt(4)
	v_mfma_f32_16x16x32_bf16 v[60:63], v[60:63], v[12:15], v[64:67]
	s_nop 2
	v_mul_f32_e32 v41, 0x3e38aa3b, v68
	v_mul_f32_e32 v72, 0x3e38aa3b, v69
	v_exp_f32_e64 v42, -|v41|
	v_exp_f32_e64 v43, -|v72|
	v_mul_f32_e32 v73, 0x3e38aa3b, v70
	v_mul_f32_e32 v74, 0x3e38aa3b, v71
	v_add_f32_e32 v42, 1.0, v42
	v_add_f32_e32 v43, 1.0, v43
	v_log_f32_e32 v42, v42
	v_log_f32_e32 v43, v43
	v_max_f32_e32 v64, 0, v41
	v_max_f32_e32 v65, 0, v72
	v_exp_f32_e64 v41, -|v73|
	v_pk_add_f32 v[78:79], v[64:65], v[42:43]
	v_exp_f32_e64 v43, -|v74|
	s_waitcnt lgkmcnt(3)
	v_mfma_f32_16x16x32_bf16 v[56:59], v[56:59], v[8:11], 0
	v_add_f32_e32 v41, 1.0, v41
	v_log_f32_e32 v42, v41
	v_add_f32_e32 v41, 1.0, v43
	v_log_f32_e32 v43, v41
	s_waitcnt lgkmcnt(1)
	v_mfma_f32_16x16x32_bf16 v[48:51], v[48:51], v[8:11], 0
	v_mul_f32_e32 v41, 0x3e38aa3b, v60
	v_mfma_f32_16x16x32_bf16 v[52:55], v[52:55], v[12:15], v[56:59]
	s_nop 2
	v_max_f32_e32 v56, 0, v73
	v_max_f32_e32 v57, 0, v74
	v_pk_add_f32 v[80:81], v[56:57], v[42:43]
	v_exp_f32_e64 v43, -|v41|
	v_max_f32_e32 v42, 0, v41
	v_mul_f32_e32 v41, 0x3e38aa3b, v61
	s_waitcnt lgkmcnt(0)
	v_mfma_f32_16x16x32_bf16 v[44:47], v[44:47], v[12:15], v[48:51]
	v_mul_f32_e32 v56, 0x3e38aa3b, v62
	v_mul_f32_e32 v57, 0x3e38aa3b, v63
	v_add_f32_e32 v43, 1.0, v43
	v_exp_f32_e64 v49, -|v41|
	v_exp_f32_e64 v50, -|v56|
	v_exp_f32_e64 v51, -|v57|
	v_log_f32_e32 v48, v43
	v_max_f32_e32 v43, 0, v41
	v_add_f32_e32 v41, 1.0, v49
	v_log_f32_e32 v49, v41
	v_add_f32_e32 v41, 1.0, v50
	v_log_f32_e32 v50, v41
	v_add_f32_e32 v41, 1.0, v51
	v_log_f32_e32 v51, v41
	v_pk_add_f32 v[82:83], v[42:43], v[48:49]
	v_max_f32_e32 v42, 0, v56
	v_max_f32_e32 v43, 0, v57
	v_mul_f32_e32 v41, 0x3e38aa3b, v52
	v_pk_add_f32 v[84:85], v[42:43], v[50:51]
	v_exp_f32_e64 v43, -|v41|
	v_max_f32_e32 v42, 0, v41
	v_mul_f32_e32 v41, 0x3e38aa3b, v53
	v_exp_f32_e64 v49, -|v41|
	v_mul_f32_e32 v56, 0x3e38aa3b, v54
	v_exp_f32_e64 v50, -|v56|
	v_mul_f32_e32 v57, 0x3e38aa3b, v55
	v_exp_f32_e64 v51, -|v57|
	v_add_f32_e32 v43, 1.0, v43
	v_log_f32_e32 v48, v43
	v_max_f32_e32 v43, 0, v41
	v_add_f32_e32 v41, 1.0, v49
	v_log_f32_e32 v49, v41
	v_add_f32_e32 v41, 1.0, v50
	v_log_f32_e32 v50, v41
	v_add_f32_e32 v41, 1.0, v51
	v_log_f32_e32 v51, v41
	v_pk_add_f32 v[86:87], v[42:43], v[48:49]
	v_max_f32_e32 v42, 0, v56
	v_max_f32_e32 v43, 0, v57
	v_mul_f32_e32 v41, 0x3e38aa3b, v44
	v_pk_add_f32 v[88:89], v[42:43], v[50:51]
	v_exp_f32_e64 v43, -|v41|
	v_max_f32_e32 v42, 0, v41
	v_mul_f32_e32 v41, 0x3e38aa3b, v45
	v_exp_f32_e64 v49, -|v41|
	v_mul_f32_e32 v56, 0x3e38aa3b, v46
	v_exp_f32_e64 v50, -|v56|
	v_mul_f32_e32 v57, 0x3e38aa3b, v47
	v_exp_f32_e64 v51, -|v57|
	v_add_f32_e32 v43, 1.0, v43
	v_log_f32_e32 v48, v43
	v_max_f32_e32 v43, 0, v41
	v_add_f32_e32 v41, 1.0, v49
	v_log_f32_e32 v49, v41
	v_add_f32_e32 v41, 1.0, v50
	v_log_f32_e32 v50, v41
	v_add_f32_e32 v41, 1.0, v51
	v_log_f32_e32 v51, v41
	v_pk_add_f32 v[90:91], v[42:43], v[48:49]
	v_max_f32_e32 v42, 0, v56
	v_max_f32_e32 v43, 0, v57
	v_mov_b64_e32 v[58:59], s[26:27]
	v_pk_add_f32 v[92:93], v[42:43], v[50:51]
	v_pk_add_f32 v[42:43], v[78:79], 0 neg_lo:[1,1] neg_hi:[1,1]
	v_mov_b64_e32 v[56:57], s[24:25]
	v_cvt_pk_bf16_f32 v48, v42, v43
	v_pk_add_f32 v[42:43], v[80:81], 0 neg_lo:[1,1] neg_hi:[1,1]
	v_mov_b32_e32 v41, v40
	v_cvt_pk_bf16_f32 v49, v42, v43
	v_pk_add_f32 v[42:43], v[82:83], 0 neg_lo:[1,1] neg_hi:[1,1]
	v_fma_f32 v46, v46, s12, -v92
	v_cvt_pk_bf16_f32 v50, v42, v43
	v_pk_add_f32 v[42:43], v[84:85], 0 neg_lo:[1,1] neg_hi:[1,1]
	v_fma_f32 v47, v47, s12, -v93
	v_cvt_pk_bf16_f32 v51, v42, v43
	v_pk_add_f32 v[42:43], v[86:87], 0 neg_lo:[1,1] neg_hi:[1,1]
	v_fma_f32 v45, v45, s12, -v91
	v_cvt_pk_bf16_f32 v64, v42, v43
	v_pk_add_f32 v[42:43], v[88:89], 0 neg_lo:[1,1] neg_hi:[1,1]
	v_mfma_f32_16x16x32_bf16 v[72:75], v[56:59], v[48:51], 0
	v_cvt_pk_bf16_f32 v65, v42, v43
	v_pk_add_f32 v[42:43], v[90:91], 0 neg_lo:[1,1] neg_hi:[1,1]
	v_fma_f32 v44, v44, s12, -v90
	v_cvt_pk_bf16_f32 v66, v42, v43
	v_pk_add_f32 v[42:43], v[92:93], 0 neg_lo:[1,1] neg_hi:[1,1]
	s_nop 0
	v_cvt_pk_bf16_f32 v67, v42, v43
	v_mov_b32_e32 v42, v40
	v_mov_b32_e32 v43, v40
	v_mfma_f32_16x16x32_bf16 v[72:75], v[56:59], v[64:67], v[72:75]
	s_nop 0
	v_mfma_f32_16x16x32_bf16 v[74:77], v[0:3], v[48:51], v[40:43]
	v_mfma_f32_16x16x32_bf16 v[48:51], v[4:7], v[48:51], v[40:43]
	v_mfma_f32_16x16x32_bf16 v[48:51], v[56:59], v[64:67], v[48:51]
	v_mfma_f32_16x16x32_bf16 v[74:77], v[56:59], v[64:67], v[74:77]
	v_mfma_f32_16x16x32_bf16 v[56:59], v[0:3], v[64:67], v[40:43]
	v_mfma_f32_16x16x32_bf16 v[64:67], v[4:7], v[64:67], v[40:43]
	s_nop 2
	v_fma_f32 v42, v53, s12, -v87
	v_fma_f32 v53, v60, s12, -v82
	v_add_f32_e32 v48, v53, v48
	v_fma_f32 v53, v61, s12, -v83
	v_add_f32_e32 v49, v53, v49
	v_fma_f32 v53, v62, s12, -v84
	v_fma_f32 v41, v52, s12, -v86
	v_add_f32_e32 v50, v53, v50
	v_fma_f32 v53, v63, s12, -v85
	v_add_f32_e32 v41, v41, v56
	v_add_f32_e32 v42, v42, v57
	v_add_f32_e32 v51, v53, v51
	v_exp_f32_e32 v41, v41
	v_exp_f32_e32 v42, v42
	v_fma_f32 v43, v54, s12, -v88
	v_fma_f32 v52, v55, s12, -v89
	v_exp_f32_e32 v50, v50
	v_exp_f32_e32 v51, v51
	v_add_f32_e32 v43, v43, v58
	v_add_f32_e32 v52, v52, v59
	v_exp_f32_e32 v43, v43
	v_exp_f32_e32 v52, v52
	v_exp_f32_e32 v48, v48
	v_exp_f32_e32 v53, v49
	v_cvt_pk_bf16_f32 v42, v41, v42
	v_cvt_pk_bf16_f32 v49, v50, v51
	v_fma_f32 v41, v68, s12, -v78
	v_fma_f32 v50, v69, s12, -v79
	v_add_f32_e32 v41, v41, v74
	v_add_f32_e32 v50, v50, v75
	v_cvt_pk_bf16_f32 v43, v43, v52
	v_exp_f32_e32 v41, v41
	v_exp_f32_e32 v50, v50
	v_fma_f32 v51, v70, s12, -v80
	v_fma_f32 v52, v71, s12, -v81
	v_add_f32_e32 v46, v46, v66
	v_cvt_pk_bf16_f32 v48, v48, v53
	v_add_f32_e32 v51, v51, v76
	v_add_f32_e32 v52, v52, v77
	v_add_f32_e32 v44, v44, v64
	v_add_f32_e32 v45, v45, v65
	v_exp_f32_e32 v53, v46
	v_add_f32_e32 v46, v47, v67
	v_exp_f32_e32 v51, v51
	v_exp_f32_e32 v52, v52
	v_exp_f32_e32 v44, v44
	v_exp_f32_e32 v45, v45
	v_exp_f32_e32 v54, v46
	v_cvt_pk_bf16_f32 v46, v41, v50
	v_lshlrev_b32_e32 v41, 1, v137
	v_add3_u32 v41, s52, v136, v41
	ds_read_b64_tr_b16 v[182:183], v41 offset:9216
	ds_read_b64_tr_b16 v[184:185], v41 offset:11520
	ds_read_b64_tr_b16 v[194:195], v41 offset:13824
	ds_read_b64_tr_b16 v[196:197], v41 offset:16128
	ds_read_b64_tr_b16 v[198:199], v41 offset:9248
	ds_read_b64_tr_b16 v[202:203], v41 offset:9280
	ds_read_b64_tr_b16 v[206:207], v41 offset:9312
	ds_read_b64_tr_b16 v[200:201], v41 offset:11552
	ds_read_b64_tr_b16 v[204:205], v41 offset:11584
	ds_read_b64_tr_b16 v[208:209], v41 offset:11616
	ds_read_b64_tr_b16 v[218:219], v41 offset:13856
	ds_read_b64_tr_b16 v[224:225], v41 offset:13888
	ds_read_b64_tr_b16 v[228:229], v41 offset:13920
	ds_read_b64_tr_b16 v[220:221], v41 offset:16160
	s_waitcnt lgkmcnt(13)
	ds_read_b64_tr_b16 v[226:227], v41 offset:16192
	s_waitcnt lgkmcnt(13)
	ds_read_b64_tr_b16 v[230:231], v41 offset:16224
	v_cvt_pk_bf16_f32 v47, v51, v52
	v_cvt_pk_bf16_f32 v44, v44, v45
	v_cvt_pk_bf16_f32 v45, v53, v54
	s_nop 0
	s_nop 0
	s_nop 0
	s_nop 0
	s_nop 0
	s_nop 0
	s_nop 0
	s_nop 0
	s_nop 0
	s_nop 0
	s_nop 0
	v_mfma_f32_16x16x32_bf16 v[36:39], v[182:185], v[46:49], v[36:39]
	s_nop 0
	s_nop 0
	s_nop 0
	s_nop 0
	s_nop 0
	s_nop 0
	v_add_f32_e32 v41, v40, v72
	s_nop 0
	s_waitcnt lgkmcnt(8)
	v_mfma_f32_16x16x32_bf16 v[32:35], v[198:201], v[46:49], v[32:35]
	s_nop 0
	s_waitcnt lgkmcnt(7)
	v_mfma_f32_16x16x32_bf16 v[28:31], v[202:205], v[46:49], v[28:31]
	s_nop 0
	s_waitcnt lgkmcnt(6)
	v_mfma_f32_16x16x32_bf16 v[24:27], v[206:209], v[46:49], v[24:27]
	v_mfma_f32_16x16x32_bf16 v[80:83], v[194:197], v[42:45], v[36:39]
	s_nop 0
	s_waitcnt lgkmcnt(2)
	v_mfma_f32_16x16x32_bf16 v[84:87], v[218:221], v[42:45], v[32:35]
	s_nop 0
	s_waitcnt lgkmcnt(1)
	v_mfma_f32_16x16x32_bf16 v[96:99], v[224:227], v[42:45], v[28:31]
	s_nop 0
	s_waitcnt lgkmcnt(0)
	v_mfma_f32_16x16x32_bf16 v[92:95], v[228:231], v[42:45], v[24:27]
	s_waitcnt lgkmcnt(0)

.LBB0_484:
	s_xor_b32 s50, s19, 1
	s_waitcnt lgkmcnt(0)
	s_barrier
	v_lshl_add_u32 v29, s50, 5, v107
	ds_read_b32 v29, v29
	s_waitcnt lgkmcnt(0)
	v_cmp_ne_u32_e32 vcc, 0, v29
	s_bcnt1_i32_b64 s90, vcc
	s_cmp_lg_u64 s[90:91], 64
	s_cselect_b64 s[8:9], -1, 0
	s_cmp_eq_u64 s[90:91], 64
	s_cbranch_scc1 .LBB0_494
	s_add_i32 s12, s14, 64
	s_cmp_ge_i32 s12, s17
	s_cbranch_scc1 .LBB0_492
	s_mov_b32 s12, 0xc3200000
	v_cmp_gt_f32_e32 vcc, s12, v28
	s_cmp_eq_u64 vcc, -1
	s_cbranch_scc1 .LBB0_492
	v_add3_u32 v29, s25, v121, v123
	ds_read_b128 v[68:71], v29
	ds_read_b128 v[72:75], v29 offset:64
	ds_read_b128 v[64:67], v29 offset:2304
	ds_read_b128 v[60:63], v29 offset:2368
	ds_read_b128 v[56:59], v29 offset:4608
	ds_read_b128 v[52:55], v29 offset:4672
	ds_read_b128 v[48:51], v29 offset:6912
	ds_read_b128 v[44:47], v29 offset:6976
	s_add_i32 s12, s14, 0x7f
	v_lshlrev_b32_e32 v29, 1, v137
	s_cmp_lt_i32 s12, s15
	s_mov_b64 s[12:13], -1
	v_add3_u32 v194, s25, v136, v29
	s_cbranch_scc1 .LBB0_489
	ds_read_b64_tr_b16 v[236:237], v194 offset:9216
	ds_read_b64_tr_b16 v[240:241], v194 offset:9248
	ds_read_b64_tr_b16 v[238:239], v194 offset:11520
	ds_read_b64_tr_b16 v[242:243], v194 offset:11552
	s_waitcnt lgkmcnt(11)
	v_mfma_f32_16x16x32_bf16 v[76:79], v[68:71], v[8:11], 0
	v_cmp_lt_i32_e32 vcc, 0, v131
	s_mov_b32 s26, s24
	s_mov_b32 s27, s24
	s_waitcnt lgkmcnt(10)
	v_mfma_f32_16x16x32_bf16 v[88:91], v[72:75], v[12:15], v[76:79]
	s_mov_b32 s25, s24
	s_mov_b64 s[12:13], 0
	s_waitcnt lgkmcnt(9)
	v_mfma_f32_16x16x32_bf16 v[76:79], v[64:67], v[8:11], 0
	s_waitcnt lgkmcnt(8)
	v_mfma_f32_16x16x32_bf16 v[84:87], v[60:63], v[12:15], v[76:79]
	s_nop 1
	v_mul_f32_e32 v29, 0x3e38aa3b, v88
	v_cndmask_b32_e32 v98, v214, v29, vcc
	v_exp_f32_e64 v29, -|v98|
	v_cmp_lt_i32_e32 vcc, 1, v131
	v_max_f32_e32 v30, 0, v98
	s_waitcnt lgkmcnt(7)
	v_mfma_f32_16x16x32_bf16 v[76:79], v[56:59], v[8:11], 0
	v_add_f32_e32 v29, 1.0, v29
	v_log_f32_e32 v88, v29
	v_mul_f32_e32 v29, 0x3e38aa3b, v89
	v_cndmask_b32_e32 v99, v214, v29, vcc
	v_exp_f32_e64 v29, -|v99|
	v_cmp_lt_i32_e32 vcc, 2, v131
	v_max_f32_e32 v31, 0, v99
	s_waitcnt lgkmcnt(6)
	v_mfma_f32_16x16x32_bf16 v[80:83], v[52:55], v[12:15], v[76:79]
	v_add_f32_e32 v29, 1.0, v29
	v_log_f32_e32 v89, v29
	v_mul_f32_e32 v29, 0x3e38aa3b, v90
	v_cndmask_b32_e32 v195, v214, v29, vcc
	v_exp_f32_e64 v29, -|v195|
	v_pk_add_f32 v[94:95], v[30:31], v[88:89]
	v_cmp_lt_i32_e32 vcc, 3, v131
	s_waitcnt lgkmcnt(5)
	v_mfma_f32_16x16x32_bf16 v[76:79], v[48:51], v[8:11], 0
	v_add_f32_e32 v29, 1.0, v29
	v_log_f32_e32 v88, v29
	v_mul_f32_e32 v29, 0x3e38aa3b, v91
	v_cndmask_b32_e32 v196, v214, v29, vcc
	v_exp_f32_e64 v29, -|v196|
	v_cmp_lt_i32_e32 vcc, 16, v131
	s_waitcnt lgkmcnt(4)
	v_mfma_f32_16x16x32_bf16 v[76:79], v[44:47], v[12:15], v[76:79]
	v_max_f32_e32 v30, 0, v195
	v_add_f32_e32 v29, 1.0, v29
	v_log_f32_e32 v89, v29
	v_mul_f32_e32 v29, 0x3e38aa3b, v84
	v_cndmask_b32_e32 v197, v214, v29, vcc
	v_exp_f32_e64 v29, -|v197|
	v_cmp_lt_i32_e32 vcc, 17, v131
	v_max_f32_e32 v31, 0, v196
	v_pk_add_f32 v[96:97], v[30:31], v[88:89]
	v_add_f32_e32 v29, 1.0, v29
	v_log_f32_e32 v84, v29
	v_mul_f32_e32 v29, 0x3e38aa3b, v85
	v_cndmask_b32_e32 v210, v214, v29, vcc
	v_exp_f32_e64 v29, -|v210|
	v_cmp_lt_i32_e32 vcc, 18, v131
	v_max_f32_e32 v30, 0, v197
	v_max_f32_e32 v31, 0, v210
	v_add_f32_e32 v29, 1.0, v29
	v_log_f32_e32 v85, v29
	v_mul_f32_e32 v29, 0x3e38aa3b, v86
	v_cndmask_b32_e32 v211, v214, v29, vcc
	v_exp_f32_e64 v29, -|v211|
	v_cmp_lt_i32_e32 vcc, 19, v131
	v_pk_add_f32 v[84:85], v[30:31], v[84:85]
	v_max_f32_e32 v30, 0, v211
	v_add_f32_e32 v29, 1.0, v29
	v_log_f32_e32 v86, v29
	v_mul_f32_e32 v29, 0x3e38aa3b, v87
	v_cndmask_b32_e32 v228, v214, v29, vcc
	v_exp_f32_e64 v29, -|v228|
	v_cmp_lt_i32_e32 vcc, 32, v131
	v_max_f32_e32 v31, 0, v228
	v_mov_b64_e32 v[90:91], s[26:27]
	v_add_f32_e32 v29, 1.0, v29
	v_log_f32_e32 v87, v29
	v_mul_f32_e32 v29, 0x3e38aa3b, v80
	v_cndmask_b32_e32 v92, v214, v29, vcc
	v_exp_f32_e64 v29, -|v92|
	v_cmp_lt_i32_e32 vcc, 33, v131
	v_pk_add_f32 v[86:87], v[30:31], v[86:87]
	v_max_f32_e32 v30, 0, v92
	v_add_f32_e32 v29, 1.0, v29
	v_log_f32_e32 v80, v29
	v_mul_f32_e32 v29, 0x3e38aa3b, v81
	v_cndmask_b32_e32 v93, v214, v29, vcc
	v_exp_f32_e64 v29, -|v93|
	v_cmp_lt_i32_e32 vcc, 34, v131
	v_max_f32_e32 v31, 0, v93
	v_mov_b64_e32 v[88:89], s[24:25]
	v_add_f32_e32 v29, 1.0, v29
	v_log_f32_e32 v81, v29
	v_mul_f32_e32 v29, 0x3e38aa3b, v82
	v_cndmask_b32_e32 v229, v214, v29, vcc
	v_exp_f32_e64 v29, -|v229|
	v_cmp_lt_i32_e32 vcc, 35, v131
	v_pk_add_f32 v[80:81], v[30:31], v[80:81]
	v_max_f32_e32 v30, 0, v229
	v_add_f32_e32 v29, 1.0, v29
	v_log_f32_e32 v82, v29
	v_mul_f32_e32 v29, 0x3e38aa3b, v83
	v_cndmask_b32_e32 v230, v214, v29, vcc
	v_exp_f32_e64 v29, -|v230|
	v_cmp_lt_i32_e32 vcc, 48, v131
	v_max_f32_e32 v31, 0, v230
	v_add_f32_e32 v29, 1.0, v29
	v_log_f32_e32 v83, v29
	v_mul_f32_e32 v29, 0x3e38aa3b, v76
	v_cndmask_b32_e32 v231, v214, v29, vcc
	v_exp_f32_e64 v29, -|v231|
	v_cmp_lt_i32_e32 vcc, 49, v131
	v_pk_add_f32 v[82:83], v[30:31], v[82:83]
	v_max_f32_e32 v30, 0, v231
	v_add_f32_e32 v29, 1.0, v29
	v_log_f32_e32 v76, v29
	v_mul_f32_e32 v29, 0x3e38aa3b, v77
	v_cndmask_b32_e32 v232, v214, v29, vcc
	v_exp_f32_e64 v29, -|v232|
	v_cmp_lt_i32_e32 vcc, 50, v131
	v_max_f32_e32 v31, 0, v232
	v_add_f32_e32 v29, 1.0, v29
	v_log_f32_e32 v77, v29
	v_mul_f32_e32 v29, 0x3e38aa3b, v78
	v_cndmask_b32_e32 v233, v214, v29, vcc
	v_exp_f32_e64 v29, -|v233|
	v_pk_add_f32 v[182:183], v[30:31], v[76:77]
	v_cmp_lt_i32_e32 vcc, 51, v131
	v_max_f32_e32 v30, 0, v233
	v_add_f32_e32 v29, 1.0, v29
	v_log_f32_e32 v76, v29
	v_mul_f32_e32 v29, 0x3e38aa3b, v79
	v_cndmask_b32_e32 v234, v214, v29, vcc
	v_exp_f32_e64 v29, -|v234|
	v_max_f32_e32 v31, 0, v234
	v_add_f32_e32 v29, 1.0, v29
	v_log_f32_e32 v77, v29
	v_mov_b32_e32 v29, v28
	v_pk_add_f32 v[184:185], v[30:31], v[76:77]
	v_pk_add_f32 v[30:31], v[94:95], 0 neg_lo:[1,1] neg_hi:[1,1]
	s_nop 0
	v_cvt_pk_bf16_f32 v198, v30, v31
	v_pk_add_f32 v[30:31], v[96:97], 0 neg_lo:[1,1] neg_hi:[1,1]
	s_nop 0
	v_cvt_pk_bf16_f32 v199, v30, v31
	v_pk_add_f32 v[30:31], v[84:85], 0 neg_lo:[1,1] neg_hi:[1,1]
	s_nop 0
	v_cvt_pk_bf16_f32 v200, v30, v31
	v_pk_add_f32 v[30:31], v[86:87], 0 neg_lo:[1,1] neg_hi:[1,1]
	s_nop 0
	v_cvt_pk_bf16_f32 v201, v30, v31
	v_pk_add_f32 v[30:31], v[80:81], 0 neg_lo:[1,1] neg_hi:[1,1]
	s_nop 0
	v_cvt_pk_bf16_f32 v76, v30, v31
	v_pk_add_f32 v[30:31], v[82:83], 0 neg_lo:[1,1] neg_hi:[1,1]
	s_nop 0
	v_cvt_pk_bf16_f32 v77, v30, v31
	v_pk_add_f32 v[30:31], v[182:183], 0 neg_lo:[1,1] neg_hi:[1,1]
	s_nop 0
	v_cvt_pk_bf16_f32 v78, v30, v31
	v_pk_add_f32 v[30:31], v[184:185], 0 neg_lo:[1,1] neg_hi:[1,1]
	s_nop 0
	v_cvt_pk_bf16_f32 v79, v30, v31
	v_mov_b32_e32 v30, v28
	v_mov_b32_e32 v31, v28
	s_nop 1
	v_mfma_f32_16x16x32_bf16 v[218:221], v[0:3], v[76:79], v[28:31]
	v_mfma_f32_16x16x32_bf16 v[206:209], v[4:7], v[198:201], v[28:31]
	v_mfma_f32_16x16x32_bf16 v[202:205], v[0:3], v[198:201], v[28:31]
	v_mfma_f32_16x16x32_bf16 v[224:227], v[4:7], v[76:79], v[28:31]
	s_nop 2
	v_sub_f32_e32 v29, v92, v80
	v_sub_f32_e32 v31, v229, v82
	v_sub_f32_e32 v80, v230, v83
	v_add_f32_e32 v31, v220, v31
	v_add_f32_e32 v80, v221, v80
	v_exp_f32_e32 v31, v31
	v_exp_f32_e32 v80, v80
	v_mfma_f32_16x16x32_bf16 v[206:209], v[88:91], v[76:79], v[206:209]
	v_sub_f32_e32 v30, v93, v81
	v_add_f32_e32 v29, v218, v29
	v_add_f32_e32 v30, v219, v30
	v_cvt_pk_bf16_f32 v93, v31, v80
	v_sub_f32_e32 v31, v211, v86
	v_sub_f32_e32 v80, v228, v87
	v_exp_f32_e32 v29, v29
	v_exp_f32_e32 v30, v30
	v_add_f32_e32 v31, v31, v208
	v_add_f32_e32 v80, v80, v209
	v_exp_f32_e32 v31, v31
	v_exp_f32_e32 v80, v80
	v_mfma_f32_16x16x32_bf16 v[202:205], v[88:91], v[76:79], v[202:205]
	v_cvt_pk_bf16_f32 v92, v29, v30
	v_sub_f32_e32 v30, v210, v85
	v_sub_f32_e32 v29, v197, v84
	v_add_f32_e32 v30, v30, v207
	v_cvt_pk_bf16_f32 v207, v31, v80
	v_sub_f32_e32 v31, v195, v96
	v_sub_f32_e32 v80, v196, v97
	v_add_f32_e32 v29, v29, v206
	v_add_f32_e32 v31, v31, v204
	v_add_f32_e32 v80, v80, v205
	v_exp_f32_e32 v29, v29
	v_exp_f32_e32 v30, v30
	v_exp_f32_e32 v31, v31
	v_exp_f32_e32 v80, v80
	v_mfma_f32_16x16x32_bf16 v[196:199], v[88:91], v[198:201], 0
	v_cvt_pk_bf16_f32 v206, v29, v30
	v_sub_f32_e32 v29, v98, v94
	v_sub_f32_e32 v30, v99, v95
	v_cvt_pk_bf16_f32 v205, v31, v80
	v_sub_f32_e32 v31, v232, v183
	v_sub_f32_e32 v80, v231, v182
	v_add_f32_e32 v29, v29, v202
	v_add_f32_e32 v30, v30, v203
	v_add_f32_e32 v80, v224, v80
	v_add_f32_e32 v31, v225, v31
	v_exp_f32_e32 v29, v29
	v_exp_f32_e32 v30, v30
	v_exp_f32_e32 v80, v80
	v_exp_f32_e32 v31, v31
	v_mfma_f32_16x16x32_bf16 v[76:79], v[88:91], v[76:79], v[196:199]
	v_cvt_pk_bf16_f32 v204, v29, v30
	v_sub_f32_e32 v29, v234, v185
	v_sub_f32_e32 v30, v233, v184
	v_cvt_pk_bf16_f32 v94, v80, v31
	s_nop 0
	s_nop 0
	s_nop 0
	ds_read_b64_tr_b16 v[96:97], v194 offset:13824
	ds_read_b64_tr_b16 v[98:99], v194 offset:16128
	v_add_f32_e32 v30, v226, v30
	v_add_f32_e32 v29, v227, v29
	v_exp_f32_e32 v30, v30
	v_exp_f32_e32 v29, v29
	s_nop 0
	s_waitcnt lgkmcnt(3)
	v_mfma_f32_16x16x32_bf16 v[80:83], v[236:239], v[204:207], v[40:43]
	ds_read_b64_tr_b16 v[236:237], v194 offset:13856
	ds_read_b64_tr_b16 v[238:239], v194 offset:16160
	v_cvt_pk_bf16_f32 v95, v30, v29
	s_nop 0
	s_nop 0
	s_waitcnt lgkmcnt(2)
	v_mfma_f32_16x16x32_bf16 v[80:83], v[96:99], v[92:95], v[80:83]
	s_nop 0
	s_nop 0
	s_nop 0
	v_add_f32_e32 v29, v28, v76
	s_nop 0
	v_mfma_f32_16x16x32_bf16 v[84:87], v[240:243], v[204:207], v[36:39]
	ds_read_b64_tr_b16 v[240:241], v194 offset:9280
	ds_read_b64_tr_b16 v[242:243], v194 offset:11584
	s_nop 0
	s_waitcnt lgkmcnt(2)
	v_mfma_f32_16x16x32_bf16 v[84:87], v[236:239], v[92:95], v[84:87]
	ds_read_b64_tr_b16 v[236:237], v194 offset:13888
	ds_read_b64_tr_b16 v[238:239], v194 offset:16192
	s_nop 0
	s_nop 0
	s_nop 0
	s_nop 0
	s_nop 0
	s_waitcnt lgkmcnt(2)
	v_mfma_f32_16x16x32_bf16 v[96:99], v[240:243], v[204:207], v[32:35]
	ds_read_b64_tr_b16 v[240:241], v194 offset:9312
	ds_read_b64_tr_b16 v[242:243], v194 offset:11616
	s_nop 0
	s_waitcnt lgkmcnt(2)
	v_mfma_f32_16x16x32_bf16 v[96:99], v[236:239], v[92:95], v[96:99]
	ds_read_b64_tr_b16 v[236:237], v194 offset:13920
	ds_read_b64_tr_b16 v[238:239], v194 offset:16224
	s_nop 0
	s_nop 0
	s_nop 0
	s_nop 0
	s_nop 0
	s_waitcnt lgkmcnt(2)
	v_mfma_f32_16x16x32_bf16 v[200:203], v[240:243], v[204:207], v[24:27]
	s_nop 0
	s_waitcnt lgkmcnt(0)
	v_mfma_f32_16x16x32_bf16 v[92:95], v[236:239], v[92:95], v[200:203]
	s_waitcnt lgkmcnt(0)
.LBB0_489:
	s_andn2_b64 vcc, exec, s[12:13]
	s_cbranch_vccnz .LBB0_491
	ds_read_b64_tr_b16 v[182:183], v194 offset:9216
	ds_read_b64_tr_b16 v[184:185], v194 offset:11520
	ds_read_b64_tr_b16 v[196:197], v194 offset:13824
	ds_read_b64_tr_b16 v[198:199], v194 offset:16128
	ds_read_b64_tr_b16 v[200:201], v194 offset:9248
	ds_read_b64_tr_b16 v[204:205], v194 offset:9280
	ds_read_b64_tr_b16 v[208:209], v194 offset:9312
	ds_read_b64_tr_b16 v[202:203], v194 offset:11552
	ds_read_b64_tr_b16 v[206:207], v194 offset:11584
	ds_read_b64_tr_b16 v[210:211], v194 offset:11616
	ds_read_b64_tr_b16 v[218:219], v194 offset:13856
	ds_read_b64_tr_b16 v[224:225], v194 offset:13888
	ds_read_b64_tr_b16 v[228:229], v194 offset:13920
	ds_read_b64_tr_b16 v[220:221], v194 offset:16160
	s_waitcnt lgkmcnt(13)
	ds_read_b64_tr_b16 v[226:227], v194 offset:16192
	s_waitcnt lgkmcnt(13)
	ds_read_b64_tr_b16 v[230:231], v194 offset:16224
	s_waitcnt lgkmcnt(15)
	v_mfma_f32_16x16x32_bf16 v[68:71], v[68:71], v[8:11], 0
	s_mov_b32 s26, s24
	s_mov_b32 s27, s24
	s_mov_b32 s25, s24
	s_waitcnt lgkmcnt(15)
	v_mfma_f32_16x16x32_bf16 v[68:71], v[72:75], v[12:15], v[68:71]
	s_mov_b32 s12, 0x3e38aa3b
	s_waitcnt lgkmcnt(15)
	v_mfma_f32_16x16x32_bf16 v[64:67], v[64:67], v[8:11], 0
	s_waitcnt lgkmcnt(15)
	v_mfma_f32_16x16x32_bf16 v[60:63], v[60:63], v[12:15], v[64:67]
	s_nop 2
	v_mul_f32_e32 v29, 0x3e38aa3b, v68
	v_mul_f32_e32 v72, 0x3e38aa3b, v69
	v_exp_f32_e64 v30, -|v29|
	v_exp_f32_e64 v31, -|v72|
	v_mul_f32_e32 v73, 0x3e38aa3b, v70
	v_mul_f32_e32 v74, 0x3e38aa3b, v71
	v_add_f32_e32 v30, 1.0, v30
	v_add_f32_e32 v31, 1.0, v31
	v_log_f32_e32 v30, v30
	v_log_f32_e32 v31, v31
	v_max_f32_e32 v64, 0, v29
	v_max_f32_e32 v65, 0, v72
	v_exp_f32_e64 v29, -|v73|
	v_pk_add_f32 v[78:79], v[64:65], v[30:31]
	v_exp_f32_e64 v31, -|v74|
	s_waitcnt lgkmcnt(15)
	v_mfma_f32_16x16x32_bf16 v[56:59], v[56:59], v[8:11], 0
	v_add_f32_e32 v29, 1.0, v29
	v_log_f32_e32 v30, v29
	v_add_f32_e32 v29, 1.0, v31
	v_log_f32_e32 v31, v29
	s_waitcnt lgkmcnt(15)
	v_mfma_f32_16x16x32_bf16 v[48:51], v[48:51], v[8:11], 0
	v_mul_f32_e32 v29, 0x3e38aa3b, v60
	v_mfma_f32_16x16x32_bf16 v[52:55], v[52:55], v[12:15], v[56:59]
	s_nop 2
	v_max_f32_e32 v56, 0, v73
	v_max_f32_e32 v57, 0, v74
	v_pk_add_f32 v[80:81], v[56:57], v[30:31]
	v_exp_f32_e64 v31, -|v29|
	v_max_f32_e32 v30, 0, v29
	v_mul_f32_e32 v29, 0x3e38aa3b, v61
	s_waitcnt lgkmcnt(15)
	v_mfma_f32_16x16x32_bf16 v[44:47], v[44:47], v[12:15], v[48:51]
	v_mul_f32_e32 v56, 0x3e38aa3b, v62
	v_mul_f32_e32 v57, 0x3e38aa3b, v63
	v_add_f32_e32 v31, 1.0, v31
	v_exp_f32_e64 v49, -|v29|
	v_exp_f32_e64 v50, -|v56|
	v_exp_f32_e64 v51, -|v57|
	v_log_f32_e32 v48, v31
	v_max_f32_e32 v31, 0, v29
	v_add_f32_e32 v29, 1.0, v49
	v_log_f32_e32 v49, v29
	v_add_f32_e32 v29, 1.0, v50
	v_log_f32_e32 v50, v29
	v_add_f32_e32 v29, 1.0, v51
	v_log_f32_e32 v51, v29
	v_pk_add_f32 v[82:83], v[30:31], v[48:49]
	v_max_f32_e32 v30, 0, v56
	v_max_f32_e32 v31, 0, v57
	v_mul_f32_e32 v29, 0x3e38aa3b, v52
	v_pk_add_f32 v[84:85], v[30:31], v[50:51]
	v_exp_f32_e64 v31, -|v29|
	v_max_f32_e32 v30, 0, v29
	v_mul_f32_e32 v29, 0x3e38aa3b, v53
	v_exp_f32_e64 v49, -|v29|
	v_mul_f32_e32 v56, 0x3e38aa3b, v54
	v_exp_f32_e64 v50, -|v56|
	v_mul_f32_e32 v57, 0x3e38aa3b, v55
	v_exp_f32_e64 v51, -|v57|
	v_add_f32_e32 v31, 1.0, v31
	v_log_f32_e32 v48, v31
	v_max_f32_e32 v31, 0, v29
	v_add_f32_e32 v29, 1.0, v49
	v_log_f32_e32 v49, v29
	v_add_f32_e32 v29, 1.0, v50
	v_log_f32_e32 v50, v29
	v_add_f32_e32 v29, 1.0, v51
	v_log_f32_e32 v51, v29
	v_pk_add_f32 v[86:87], v[30:31], v[48:49]
	v_max_f32_e32 v30, 0, v56
	v_max_f32_e32 v31, 0, v57
	v_mul_f32_e32 v29, 0x3e38aa3b, v44
	v_pk_add_f32 v[88:89], v[30:31], v[50:51]
	v_exp_f32_e64 v31, -|v29|
	v_max_f32_e32 v30, 0, v29
	v_mul_f32_e32 v29, 0x3e38aa3b, v45
	v_exp_f32_e64 v49, -|v29|
	v_mul_f32_e32 v56, 0x3e38aa3b, v46
	v_exp_f32_e64 v50, -|v56|
	v_mul_f32_e32 v57, 0x3e38aa3b, v47
	v_exp_f32_e64 v51, -|v57|
	v_add_f32_e32 v31, 1.0, v31
	v_log_f32_e32 v48, v31
	v_max_f32_e32 v31, 0, v29
	v_add_f32_e32 v29, 1.0, v49
	v_log_f32_e32 v49, v29
	v_add_f32_e32 v29, 1.0, v50
	v_log_f32_e32 v50, v29
	v_add_f32_e32 v29, 1.0, v51
	v_log_f32_e32 v51, v29
	v_pk_add_f32 v[90:91], v[30:31], v[48:49]
	v_max_f32_e32 v30, 0, v56
	v_max_f32_e32 v31, 0, v57
	v_mov_b64_e32 v[58:59], s[26:27]
	v_pk_add_f32 v[92:93], v[30:31], v[50:51]
	v_pk_add_f32 v[30:31], v[78:79], 0 neg_lo:[1,1] neg_hi:[1,1]
	v_mov_b64_e32 v[56:57], s[24:25]
	v_cvt_pk_bf16_f32 v48, v30, v31
	v_pk_add_f32 v[30:31], v[80:81], 0 neg_lo:[1,1] neg_hi:[1,1]
	v_mov_b32_e32 v29, v28
	v_cvt_pk_bf16_f32 v49, v30, v31
	v_pk_add_f32 v[30:31], v[82:83], 0 neg_lo:[1,1] neg_hi:[1,1]
	v_fma_f32 v47, v47, s12, -v93
	v_cvt_pk_bf16_f32 v50, v30, v31
	v_pk_add_f32 v[30:31], v[84:85], 0 neg_lo:[1,1] neg_hi:[1,1]
	v_fma_f32 v46, v46, s12, -v92
	v_cvt_pk_bf16_f32 v51, v30, v31
	v_pk_add_f32 v[30:31], v[86:87], 0 neg_lo:[1,1] neg_hi:[1,1]
	v_fma_f32 v45, v45, s12, -v91
	v_cvt_pk_bf16_f32 v64, v30, v31
	v_pk_add_f32 v[30:31], v[88:89], 0 neg_lo:[1,1] neg_hi:[1,1]
	v_mfma_f32_16x16x32_bf16 v[72:75], v[56:59], v[48:51], 0
	v_cvt_pk_bf16_f32 v65, v30, v31
	v_pk_add_f32 v[30:31], v[90:91], 0 neg_lo:[1,1] neg_hi:[1,1]
	v_fma_f32 v44, v44, s12, -v90
	v_cvt_pk_bf16_f32 v66, v30, v31
	v_pk_add_f32 v[30:31], v[92:93], 0 neg_lo:[1,1] neg_hi:[1,1]
	s_nop 0
	v_cvt_pk_bf16_f32 v67, v30, v31
	v_mov_b32_e32 v30, v28
	v_mov_b32_e32 v31, v28
	v_mfma_f32_16x16x32_bf16 v[72:75], v[56:59], v[64:67], v[72:75]
	s_nop 0
	v_mfma_f32_16x16x32_bf16 v[74:77], v[0:3], v[48:51], v[28:31]
	v_mfma_f32_16x16x32_bf16 v[48:51], v[4:7], v[48:51], v[28:31]
	v_mfma_f32_16x16x32_bf16 v[48:51], v[56:59], v[64:67], v[48:51]
	v_mfma_f32_16x16x32_bf16 v[74:77], v[56:59], v[64:67], v[74:77]
	v_mfma_f32_16x16x32_bf16 v[56:59], v[0:3], v[64:67], v[28:31]
	v_mfma_f32_16x16x32_bf16 v[64:67], v[4:7], v[64:67], v[28:31]
	s_nop 2
	v_fma_f32 v30, v53, s12, -v87
	v_fma_f32 v53, v60, s12, -v82
	v_add_f32_e32 v48, v53, v48
	v_exp_f32_e32 v53, v48
	v_fma_f32 v48, v61, s12, -v83
	v_add_f32_e32 v48, v48, v49
	v_fma_f32 v49, v62, s12, -v84
	v_add_f32_e32 v49, v49, v50
	v_fma_f32 v29, v52, s12, -v86
	v_fma_f32 v31, v54, s12, -v88
	v_fma_f32 v52, v55, s12, -v89
	v_exp_f32_e32 v50, v49
	v_fma_f32 v49, v63, s12, -v85
	v_add_f32_e32 v31, v31, v58
	v_add_f32_e32 v52, v52, v59
	v_add_f32_e32 v49, v49, v51
	v_exp_f32_e32 v31, v31
	v_exp_f32_e32 v52, v52
	v_exp_f32_e32 v51, v49
	v_add_f32_e32 v29, v29, v56
	v_add_f32_e32 v30, v30, v57
	v_exp_f32_e32 v29, v29
	v_exp_f32_e32 v30, v30
	v_cvt_pk_bf16_f32 v49, v31, v52
	v_cvt_pk_bf16_f32 v55, v50, v51
	v_fma_f32 v31, v70, s12, -v80
	v_fma_f32 v50, v71, s12, -v81
	v_add_f32_e32 v31, v31, v76
	v_add_f32_e32 v50, v50, v77
	v_add_f32_e32 v44, v44, v64
	v_add_f32_e32 v45, v45, v65
	v_add_f32_e32 v46, v46, v66
	v_add_f32_e32 v47, v47, v67
	v_exp_f32_e32 v54, v48
	v_exp_f32_e32 v31, v31
	v_exp_f32_e32 v50, v50
	v_exp_f32_e32 v44, v44
	v_exp_f32_e32 v45, v45
	v_exp_f32_e32 v46, v46
	v_exp_f32_e32 v47, v47
	v_cvt_pk_bf16_f32 v48, v29, v30
	v_fma_f32 v29, v68, s12, -v78
	v_fma_f32 v30, v69, s12, -v79
	v_add_f32_e32 v29, v29, v74
	v_add_f32_e32 v30, v30, v75
	v_exp_f32_e32 v29, v29
	v_exp_f32_e32 v30, v30
	v_cvt_pk_bf16_f32 v54, v53, v54
	v_cvt_pk_bf16_f32 v53, v31, v50
	v_cvt_pk_bf16_f32 v50, v44, v45
	v_cvt_pk_bf16_f32 v51, v46, v47
	s_nop 0
	s_nop 0
	s_nop 0
	s_nop 0
	s_nop 0
	s_nop 0
	s_nop 0
	s_nop 0
	s_nop 0
	s_nop 0
	v_cvt_pk_bf16_f32 v52, v29, v30
	v_add_f32_e32 v29, v28, v72
	s_nop 0
	v_mfma_f32_16x16x32_bf16 v[40:43], v[182:185], v[52:55], v[40:43]
	s_nop 0
	s_nop 0
	s_nop 0
	s_nop 0
	s_nop 0
	s_nop 0
	s_nop 0
	s_waitcnt lgkmcnt(8)
	v_mfma_f32_16x16x32_bf16 v[36:39], v[200:203], v[52:55], v[36:39]
	s_nop 0
	s_waitcnt lgkmcnt(7)
	v_mfma_f32_16x16x32_bf16 v[30:33], v[204:207], v[52:55], v[32:35]
	s_nop 0
	s_waitcnt lgkmcnt(6)
	v_mfma_f32_16x16x32_bf16 v[24:27], v[208:211], v[52:55], v[24:27]
	v_mfma_f32_16x16x32_bf16 v[80:83], v[196:199], v[48:51], v[40:43]
	s_nop 0
	s_waitcnt lgkmcnt(2)
	v_mfma_f32_16x16x32_bf16 v[84:87], v[218:221], v[48:51], v[36:39]
	s_nop 0
	s_waitcnt lgkmcnt(1)
	v_mfma_f32_16x16x32_bf16 v[96:99], v[224:227], v[48:51], v[30:33]
	s_nop 0
	s_waitcnt lgkmcnt(0)
	v_mfma_f32_16x16x32_bf16 v[92:95], v[228:231], v[48:51], v[24:27]
	s_waitcnt lgkmcnt(0)

.LBB0_566:
	s_or_b64 exec, exec, s[14:15]
	s_waitcnt vmcnt(1)
	ds_write_b128 v146, v[32:35] offset:34816
	s_waitcnt vmcnt(0)
	ds_write_b128 v146, v[28:31] offset:34832
	ds_read_b128 v[52:55], v161
	ds_read_b128 v[56:59], v161 offset:16
	ds_read_b128 v[60:63], v162
	ds_read_b128 v[64:67], v162 offset:16
	ds_read_b128 v[68:71], v162 offset:512
	ds_read_b128 v[72:75], v162 offset:528
	ds_read_b128 v[76:79], v162 offset:1024
	ds_read_b128 v[88:91], v162 offset:1040
	ds_read_b128 v[132:135], v162 offset:1536
	ds_read_b128 v[182:185], v162 offset:1552
	s_nop 0
	s_nop 0
	s_nop 0
	s_waitcnt lgkmcnt(13)
	s_nop 0
	v_lshlrev_b32_e32 v36, 16, v24
	v_and_b32_e32 v37, 0xffff0000, v24
	v_lshlrev_b32_e32 v24, 16, v25
	v_and_b32_e32 v25, 0xffff0000, v25
	s_nop 0
	s_waitcnt lgkmcnt(7)
	v_pk_fma_f32 v[30:31], v[62:63], v[24:25], v[54:55]
	v_lshlrev_b32_e32 v24, 16, v26
	v_and_b32_e32 v25, 0xffff0000, v26
	v_lshlrev_b32_e32 v26, 16, v27
	v_and_b32_e32 v27, 0xffff0000, v27
	v_pk_fma_f32 v[36:37], v[60:61], v[36:37], v[52:53]
	s_nop 0
	s_waitcnt lgkmcnt(6)
	v_pk_fma_f32 v[34:35], v[66:67], v[26:27], v[58:59]
	s_nop 0
	v_pk_fma_f32 v[32:33], v[64:65], v[24:25], v[56:57]
	v_lshlrev_b32_e32 v24, 16, v20
	v_and_b32_e32 v25, 0xffff0000, v20
	v_lshlrev_b32_e32 v20, 16, v21
	v_and_b32_e32 v21, 0xffff0000, v21
	s_nop 0
	s_waitcnt lgkmcnt(5)
	v_pk_fma_f32 v[40:41], v[70:71], v[20:21], v[30:31]
	s_nop 0
	v_pk_fma_f32 v[36:37], v[68:69], v[24:25], v[36:37]
	v_lshlrev_b32_e32 v26, 16, v22
	v_and_b32_e32 v27, 0xffff0000, v22
	v_lshlrev_b32_e32 v22, 16, v23
	v_and_b32_e32 v23, 0xffff0000, v23
	s_nop 0
	s_waitcnt lgkmcnt(4)
	v_pk_fma_f32 v[42:43], v[74:75], v[22:23], v[34:35]
	v_pk_fma_f32 v[44:45], v[72:73], v[26:27], v[32:33]
	s_nop 0
	v_lshlrev_b32_e32 v28, 16, v16
	v_and_b32_e32 v29, 0xffff0000, v16
	v_lshlrev_b32_e32 v30, 16, v17
	v_and_b32_e32 v31, 0xffff0000, v17
	s_nop 0
	s_waitcnt lgkmcnt(3)
	v_pk_fma_f32 v[46:47], v[76:77], v[28:29], v[36:37]
	v_pk_fma_f32 v[48:49], v[78:79], v[30:31], v[40:41]
	s_nop 0
	v_lshlrev_b32_e32 v16, 16, v18
	v_and_b32_e32 v17, 0xffff0000, v18
	v_lshlrev_b32_e32 v18, 16, v19
	v_and_b32_e32 v19, 0xffff0000, v19
	s_nop 0
	s_waitcnt lgkmcnt(2)
	v_pk_fma_f32 v[50:51], v[90:91], v[18:19], v[42:43]
	s_nop 0
	v_lshlrev_b32_e32 v34, 16, v12
	v_and_b32_e32 v35, 0xffff0000, v12
	v_lshlrev_b32_e32 v36, 16, v13
	v_and_b32_e32 v37, 0xffff0000, v13
	s_nop 0
	s_waitcnt lgkmcnt(1)
	v_pk_fma_f32 v[48:49], v[134:135], v[36:37], v[48:49]
	v_pk_fma_f32 v[46:47], v[132:133], v[34:35], v[46:47]
	s_nop 0
	v_lshlrev_b32_e32 v12, 16, v15
	v_and_b32_e32 v13, 0xffff0000, v15
	v_pk_fma_f32 v[44:45], v[88:89], v[16:17], v[44:45]
	v_lshlrev_b32_e32 v32, 16, v14
	v_and_b32_e32 v33, 0xffff0000, v14
	s_nop 0
	s_waitcnt lgkmcnt(0)
	v_pk_fma_f32 v[14:15], v[184:185], v[12:13], v[50:51]
	v_mul_f32_e32 v42, 0xbfb8aa3b, v46
	v_mul_f32_e32 v43, 0xbfb8aa3b, v47
	v_exp_f32_e32 v42, v42
	v_exp_f32_e32 v43, v43
	v_pk_fma_f32 v[40:41], v[182:183], v[32:33], v[44:45]
	v_mul_f32_e32 v44, 0xbfb8aa3b, v48
	v_add_f32_e32 v42, 1.0, v42
	v_add_f32_e32 v43, 1.0, v43
	v_rcp_f32_e32 v42, v42
	v_rcp_f32_e32 v43, v43
	v_mul_f32_e32 v45, 0xbfb8aa3b, v49
	v_exp_f32_e32 v44, v44
	v_exp_f32_e32 v45, v45
	v_pk_mul_f32 v[42:43], v[46:47], v[42:43]
	v_mul_f32_e32 v46, 0xbfb8aa3b, v40
	v_mul_f32_e32 v47, 0xbfb8aa3b, v41
	v_exp_f32_e32 v46, v46
	v_exp_f32_e32 v47, v47
	v_add_f32_e32 v44, 1.0, v44
	v_add_f32_e32 v45, 1.0, v45
	v_add_f32_e32 v46, 1.0, v46
	v_add_f32_e32 v47, 1.0, v47
	v_rcp_f32_e32 v46, v46
	v_rcp_f32_e32 v47, v47
	v_rcp_f32_e32 v44, v44
	v_rcp_f32_e32 v45, v45
	s_waitcnt lgkmcnt(0)
	s_and_b64 vcc, exec, s[12:13]
	v_pk_mul_f32 v[46:47], v[40:41], v[46:47]
	v_mul_f32_e32 v40, 0xbfb8aa3b, v14
	v_mul_f32_e32 v41, 0xbfb8aa3b, v15
	v_exp_f32_e32 v40, v40
	v_exp_f32_e32 v41, v41
	v_pk_mul_f32 v[44:45], v[48:49], v[44:45]
	v_add_f32_e32 v40, 1.0, v40
	v_add_f32_e32 v41, 1.0, v41
	v_rcp_f32_e32 v40, v40
	v_rcp_f32_e32 v41, v41
	s_nop 0
	v_pk_mul_f32 v[14:15], v[14:15], v[40:41]
	v_cvt_pk_bf16_f32 v40, v42, v43
	v_cvt_pk_bf16_f32 v41, v44, v45
	v_cvt_pk_bf16_f32 v42, v46, v47
	v_cvt_pk_bf16_f32 v43, v14, v15
	ds_write_b128 v177, v[40:43] offset:17408
	ds_read_b128 v[56:59], v161
	ds_read_b128 v[60:63], v161 offset:16
	ds_read_b128 v[64:67], v162
	ds_read_b128 v[68:71], v162 offset:16
	ds_read_b128 v[72:75], v162 offset:512
	ds_read_b128 v[76:79], v162 offset:528
	ds_read_b128 v[88:91], v162 offset:1024
	ds_read_b128 v[132:135], v162 offset:1040
	ds_read_b128 v[182:185], v162 offset:1536
	ds_read_b128 v[192:195], v162 offset:1552
	s_nop 0
	s_nop 0
	s_nop 0
	s_nop 0
	s_nop 0
	s_waitcnt lgkmcnt(7)
	v_pk_fma_f32 v[14:15], v[64:65], v[24:25], v[56:57]
	v_pk_fma_f32 v[24:25], v[66:67], v[20:21], v[58:59]
	s_nop 0
	s_waitcnt lgkmcnt(6)
	v_pk_fma_f32 v[40:41], v[70:71], v[22:23], v[62:63]
	s_nop 0
	v_pk_fma_f32 v[26:27], v[68:69], v[26:27], v[60:61]
	s_nop 0
	s_waitcnt lgkmcnt(5)
	v_pk_fma_f32 v[24:25], v[74:75], v[30:31], v[24:25]
	v_pk_fma_f32 v[28:29], v[72:73], v[28:29], v[14:15]
	s_nop 0
	s_nop 0
	s_waitcnt lgkmcnt(4)
	v_pk_fma_f32 v[20:21], v[76:77], v[16:17], v[26:27]
	s_nop 0
	v_pk_fma_f32 v[18:19], v[78:79], v[18:19], v[40:41]
	s_nop 0
	s_waitcnt lgkmcnt(3)
	v_pk_fma_f32 v[22:23], v[88:89], v[34:35], v[28:29]
	v_pk_fma_f32 v[24:25], v[90:91], v[36:37], v[24:25]
	s_nop 0
	s_nop 0
	s_waitcnt lgkmcnt(2)
	v_pk_fma_f32 v[20:21], v[132:133], v[32:33], v[20:21]
	v_pk_fma_f32 v[16:17], v[134:135], v[12:13], v[18:19]
	s_nop 0
	v_lshlrev_b32_e32 v18, 16, v8
	v_and_b32_e32 v19, 0xffff0000, v8
	v_lshlrev_b32_e32 v8, 16, v9
	v_and_b32_e32 v9, 0xffff0000, v9
	s_nop 0
	s_waitcnt lgkmcnt(1)
	v_pk_fma_f32 v[14:15], v[184:185], v[8:9], v[24:25]
	v_pk_fma_f32 v[12:13], v[182:183], v[18:19], v[22:23]
	v_lshlrev_b32_e32 v18, 16, v10
	v_and_b32_e32 v19, 0xffff0000, v10
	v_lshlrev_b32_e32 v22, 16, v11
	v_and_b32_e32 v23, 0xffff0000, v11
	s_nop 0
	s_nop 0
	s_waitcnt lgkmcnt(0)
	v_pk_fma_f32 v[10:11], v[194:195], v[22:23], v[16:17]
	v_mul_f32_e32 v16, 0xbfb8aa3b, v12
	v_mul_f32_e32 v17, 0xbfb8aa3b, v13
	v_exp_f32_e32 v16, v16
	v_exp_f32_e32 v17, v17
	v_pk_fma_f32 v[8:9], v[192:193], v[18:19], v[20:21]
	v_add_f32_e32 v16, 1.0, v16
	v_add_f32_e32 v17, 1.0, v17
	v_rcp_f32_e32 v16, v16
	v_rcp_f32_e32 v17, v17
	s_nop 0
	v_pk_mul_f32 v[12:13], v[12:13], v[16:17]
	v_mul_f32_e32 v16, 0xbfb8aa3b, v14
	v_mul_f32_e32 v17, 0xbfb8aa3b, v15
	v_exp_f32_e32 v16, v16
	v_exp_f32_e32 v17, v17
	v_add_f32_e32 v16, 1.0, v16
	v_add_f32_e32 v17, 1.0, v17
	v_rcp_f32_e32 v16, v16
	v_rcp_f32_e32 v17, v17
	s_nop 0
	v_pk_mul_f32 v[14:15], v[14:15], v[16:17]
	v_mul_f32_e32 v16, 0xbfb8aa3b, v8
	v_mul_f32_e32 v17, 0xbfb8aa3b, v9
	v_exp_f32_e32 v16, v16
	v_exp_f32_e32 v17, v17
	v_add_f32_e32 v16, 1.0, v16
	v_add_f32_e32 v17, 1.0, v17
	v_rcp_f32_e32 v16, v16
	v_rcp_f32_e32 v17, v17
	s_nop 0
	v_pk_mul_f32 v[16:17], v[8:9], v[16:17]
	v_mul_f32_e32 v8, 0xbfb8aa3b, v10
	v_mul_f32_e32 v9, 0xbfb8aa3b, v11
	v_exp_f32_e32 v8, v8
	v_exp_f32_e32 v9, v9
	v_add_f32_e32 v8, 1.0, v8
	v_add_f32_e32 v9, 1.0, v9
	v_rcp_f32_e32 v8, v8
	v_rcp_f32_e32 v9, v9
	s_nop 0
	v_pk_mul_f32 v[18:19], v[10:11], v[8:9]
	v_cvt_pk_bf16_f32 v8, v12, v13
	v_cvt_pk_bf16_f32 v9, v14, v15
	v_cvt_pk_bf16_f32 v10, v16, v17
	v_cvt_pk_bf16_f32 v11, v18, v19
	ds_write_b128 v178, v[8:11] offset:17408
	s_waitcnt lgkmcnt(0)
	s_cbranch_vccnz .LBB0_570
	v_and_b32_e32 v8, 64, v216
	v_add_u32_e32 v9, -1, v216
	v_cmp_lt_i32_e32 vcc, v9, v8
	v_add_u32_e32 v11, -2, v216
	v_readlane_b32 s12, v254, 57
	v_cndmask_b32_e32 v9, v9, v216, vcc
	v_lshlrev_b32_e32 v9, 2, v9
	ds_bpermute_b32 v10, v9, v39
	v_cmp_lt_i32_e32 vcc, v11, v8
	v_readlane_b32 s13, v254, 58
	v_readlane_b32 s14, v254, 59
	v_cndmask_b32_e32 v11, v11, v216, vcc
	s_waitcnt lgkmcnt(0)
	v_add_f32_e32 v10, v39, v10
	v_cndmask_b32_e64 v10, v10, v39, s[48:49]
	v_lshlrev_b32_e32 v11, 2, v11
	ds_bpermute_b32 v12, v11, v10
	v_readlane_b32 s15, v254, 60
	v_readlane_b32 s16, v254, 61
	v_readlane_b32 s17, v254, 62
	v_readlane_b32 s18, v254, 63
	s_waitcnt lgkmcnt(0)
	v_add_f32_e32 v12, v10, v12
	v_cndmask_b32_e64 v10, v12, v10, s[12:13]
	v_add_u32_e32 v12, -4, v216
	v_cmp_lt_i32_e32 vcc, v12, v8
	v_readlane_b32 s19, v255, 0
	s_nop 0
	v_cndmask_b32_e32 v12, v12, v216, vcc
	v_lshlrev_b32_e32 v12, 2, v12
	ds_bpermute_b32 v13, v12, v10
	s_waitcnt lgkmcnt(0)
	v_add_f32_e32 v13, v10, v13
	v_cndmask_b32_e64 v10, v13, v10, s[14:15]
	v_add_u32_e32 v13, -8, v216
	v_cmp_lt_i32_e32 vcc, v13, v8
	s_nop 1
	v_cndmask_b32_e32 v13, v13, v216, vcc
	v_lshlrev_b32_e32 v13, 2, v13
	ds_bpermute_b32 v14, v13, v10
	s_waitcnt lgkmcnt(0)
	v_add_f32_e32 v14, v10, v14
	v_cndmask_b32_e64 v10, v14, v10, s[16:17]
	v_add_u32_e32 v14, -16, v216
	v_cmp_lt_i32_e32 vcc, v14, v8
	s_nop 1
	v_cndmask_b32_e32 v14, v14, v216, vcc
	v_lshlrev_b32_e32 v14, 2, v14
	ds_bpermute_b32 v15, v14, v10
	s_waitcnt lgkmcnt(0)
	v_add_f32_e32 v15, v10, v15
	v_cndmask_b32_e64 v10, v15, v10, s[68:69]
	v_subrev_u32_e32 v15, 32, v216
	v_cmp_lt_i32_e32 vcc, v15, v8
	s_nop 1
	v_cndmask_b32_e32 v8, v15, v216, vcc
	v_lshlrev_b32_e32 v8, 2, v8
	ds_bpermute_b32 v15, v8, v10
	s_waitcnt lgkmcnt(0)
	v_add_f32_e32 v15, v10, v15
	v_cndmask_b32_e64 v15, v15, v10, s[18:19]
	v_sub_f32_e32 v10, v38, v15
	ds_bpermute_b32 v9, v9, v10
	s_waitcnt lgkmcnt(0)
	v_max_f32_e32 v9, v9, v9
	v_max_f32_e32 v9, v10, v9
	v_cndmask_b32_e64 v9, v9, v10, s[48:49]
	ds_bpermute_b32 v11, v11, v9
	s_waitcnt lgkmcnt(0)
	v_max_f32_e32 v11, v11, v11
	v_max_f32_e32 v11, v9, v11
	v_cndmask_b32_e64 v9, v11, v9, s[12:13]
	ds_bpermute_b32 v11, v12, v9
	s_waitcnt lgkmcnt(0)
	v_max_f32_e32 v11, v11, v11
	v_max_f32_e32 v11, v9, v11
	v_cndmask_b32_e64 v9, v11, v9, s[14:15]
	ds_bpermute_b32 v11, v13, v9
	s_waitcnt lgkmcnt(0)
	v_max_f32_e32 v11, v11, v11
	v_max_f32_e32 v11, v9, v11
	v_cndmask_b32_e64 v9, v11, v9, s[16:17]
	ds_bpermute_b32 v11, v14, v9
	s_waitcnt lgkmcnt(0)
	v_max_f32_e32 v11, v11, v11
	v_max_f32_e32 v11, v9, v11
	v_cndmask_b32_e64 v9, v11, v9, s[68:69]
	ds_bpermute_b32 v8, v8, v9
	v_max_f32_e32 v11, v9, v9
	s_waitcnt lgkmcnt(0)
	v_max_f32_e32 v8, v8, v8
	v_max_f32_e32 v8, v11, v8
	v_cndmask_b32_e64 v9, v8, v9, s[18:19]
	v_bfrev_b32_e32 v8, 0.5
	v_lshl_or_b32 v11, v216, 2, v8
	ds_bpermute_b32 v8, v11, v15
	ds_bpermute_b32 v11, v11, v9
	s_waitcnt lgkmcnt(0)
	v_pk_add_f32 v[10:11], v[10:11], v[8:9] op_sel_hi:[1,0]
	s_nop 0
	v_sub_f32_e32 v9, v10, v11
	v_mul_f32_e32 v9, 0x3fb8aa3b, v9
	v_exp_f32_e32 v9, v9
	ds_write_b32 v163, v9
	s_and_saveexec_b64 s[12:13], s[48:49]
	s_cbranch_execz .LBB0_569
	s_ashr_i32 s9, s8, 31
	s_lshl_b64 s[8:9], s[8:9], 2
	s_add_u32 s14, s67, s8
	v_readlane_b32 s15, v251, 51
	s_addc_u32 s15, s15, s9
	s_add_u32 s8, s34, s8
	v_readlane_b32 s16, v251, 52
	s_addc_u32 s9, s16, s9
	s_nop 0
	global_store_dword v181, v11, s[14:15]
	global_store_dword v181, v8, s[8:9]
